# first tile of up-projection and K|V|Q phases: barrier generation word read early by thread 0, wait before first store usually needs no fresh load
# baseline (speedup 1.0000x reference)
.LBB0_287:
	s_ashr_i32 s21, s20, 31
	s_lshl_b64 s[22:23], s[20:21], 19
	s_add_u32 s22, s80, s22
	s_addc_u32 s23, s81, s23
	s_and_b64 s[24:25], s[6:7], exec
	s_cselect_b32 s21, s23, s29
	s_cselect_b32 s36, s22, s28
	s_ashr_i32 s19, s18, 31
	s_lshl_b64 s[24:25], s[18:19], 19
	s_add_u32 s24, s40, s24
	s_addc_u32 s25, s41, s25
	s_and_b64 s[34:35], s[6:7], exec
	s_cselect_b32 s19, s25, s31
	s_cselect_b32 s37, s24, s30
	s_add_u32 s38, s30, 0x100
	s_addc_u32 s39, s31, 0
	s_add_u32 s28, s28, 0x40080
	s_addc_u32 s29, s29, 0
	s_mov_b32 s55, -2
	s_cmp_lg_u32 s9, 0
	s_cbranch_scc1 .Lkq_pfx_skip
	s_and_saveexec_b64 s[100:101], s[4:5]
	s_cbranch_execz .Lkq_pfx_rest
	s_getreg_b32 s62, hwreg(HW_REG_XCC_ID, 0, 4)
	s_lshl_b32 s62, s62, 8
	s_and_b32 s62, s62, 0xf00
	s_add_u32 s62, s0, s62
	s_addc_u32 s63, s1, 0
	global_load_dword v219, v227, s[62:63] offset:1024 sc1
.Lkq_pfx_rest:
	s_or_b64 exec, exec, s[100:101]
.Lkq_pfx_skip:
	s_add_u32 s30, s28, 0xfffc0080
	s_addc_u32 s31, s29, -1
	s_add_i32 s56, 0, 0x10000
	s_cmp_eq_u32 s55, 12
	s_cselect_b32 s35, s21, s31
	s_cselect_b32 s34, s36, s30
	s_cselect_b32 s31, s19, s39
	s_cselect_b32 s30, s37, s38
	s_add_i32 s58, 0, 0x14000
	v_add_u32_e32 v166, s56, v147
	v_add_u32_e32 v182, s58, v147
	ds_read_b128 v[142:145], v166
	ds_read_b128 v[158:161], v166 offset:1024
	ds_read_b128 v[162:165], v166 offset:2048
	ds_read_b128 v[166:169], v166 offset:3072
	ds_read_b128 v[170:173], v182
	ds_read_b128 v[174:177], v182 offset:1024
	ds_read_b128 v[178:181], v182 offset:2048
	ds_read_b128 v[182:185], v182 offset:3072
	v_lshl_add_u64 v[224:225], s[28:29], 0, v[140:141]
	s_add_i32 m0, s44, 0xc000
	ds_read_b128 v[186:189], v157
	ds_read_b128 v[190:193], v157 offset:1024
	ds_read_b128 v[194:197], v157 offset:2048
	ds_read_b128 v[198:201], v157 offset:3072
	ds_read_b128 v[202:205], v157 offset:4096
	ds_read_b128 v[206:209], v157 offset:5120
	ds_read_b128 v[220:223], v157 offset:6144
	ds_read_b128 v[236:239], v157 offset:7168
	global_load_lds_dwordx4 v[224:225], off
	v_lshl_add_u64 v[224:225], s[28:29], 0, v[138:139]
	s_add_i32 m0, s44, 0xe000
	s_nop 0
	global_load_lds_dwordx4 v[224:225], off
	s_nop 0
	s_nop 0
	s_nop 0
	s_nop 0
	s_nop 0
	s_nop 0
	s_nop 0
	s_nop 0
	s_nop 0
	s_nop 0
	s_nop 0
	s_nop 0
	s_nop 0
	s_nop 0
	s_nop 0
	s_nop 0
	s_nop 0
	s_nop 0
	s_nop 0
	s_nop 0
	s_nop 0
	s_nop 0
	s_waitcnt vmcnt(8)
	s_waitcnt lgkmcnt(0)
	s_barrier
	s_waitcnt lgkmcnt(0)
	v_mfma_f32_16x16x32_bf16 v[126:129], v[142:145], v[186:189], 0
	v_mfma_f32_16x16x32_bf16 v[122:125], v[162:165], v[186:189], 0
	v_mfma_f32_16x16x32_bf16 v[110:113], v[142:145], v[194:197], 0
	v_mfma_f32_16x16x32_bf16 v[106:109], v[162:165], v[194:197], 0
	v_mfma_f32_16x16x32_bf16 v[94:97], v[142:145], v[202:205], 0
	v_mfma_f32_16x16x32_bf16 v[90:93], v[162:165], v[202:205], 0
	v_mfma_f32_16x16x32_bf16 v[78:81], v[142:145], v[220:223], 0
	v_mfma_f32_16x16x32_bf16 v[74:77], v[162:165], v[220:223], 0
	v_mfma_f32_16x16x32_bf16 v[126:129], v[158:161], v[190:193], v[126:129]
	v_mfma_f32_16x16x32_bf16 v[122:125], v[166:169], v[190:193], v[122:125]
	v_mfma_f32_16x16x32_bf16 v[110:113], v[158:161], v[198:201], v[110:113]
	v_mfma_f32_16x16x32_bf16 v[106:109], v[166:169], v[198:201], v[106:109]
	v_mfma_f32_16x16x32_bf16 v[94:97], v[158:161], v[206:209], v[94:97]
	v_mfma_f32_16x16x32_bf16 v[90:93], v[166:169], v[206:209], v[90:93]
	v_mfma_f32_16x16x32_bf16 v[78:81], v[158:161], v[236:239], v[78:81]
	v_mfma_f32_16x16x32_bf16 v[74:77], v[166:169], v[236:239], v[74:77]
	v_mfma_f32_16x16x32_bf16 v[118:121], v[170:173], v[186:189], 0
	v_mfma_f32_16x16x32_bf16 v[114:117], v[178:181], v[186:189], 0
	v_mfma_f32_16x16x32_bf16 v[102:105], v[170:173], v[194:197], 0
	v_mfma_f32_16x16x32_bf16 v[98:101], v[178:181], v[194:197], 0
	v_mfma_f32_16x16x32_bf16 v[86:89], v[170:173], v[202:205], 0
	v_mfma_f32_16x16x32_bf16 v[82:85], v[178:181], v[202:205], 0
	v_mfma_f32_16x16x32_bf16 v[70:73], v[170:173], v[220:223], 0
	v_mfma_f32_16x16x32_bf16 v[66:69], v[178:181], v[220:223], 0
	v_mfma_f32_16x16x32_bf16 v[118:121], v[174:177], v[190:193], v[118:121]
	v_mfma_f32_16x16x32_bf16 v[114:117], v[182:185], v[190:193], v[114:117]
	v_mfma_f32_16x16x32_bf16 v[102:105], v[174:177], v[198:201], v[102:105]
	v_mfma_f32_16x16x32_bf16 v[98:101], v[182:185], v[198:201], v[98:101]
	v_mfma_f32_16x16x32_bf16 v[86:89], v[174:177], v[206:209], v[86:89]
	v_mfma_f32_16x16x32_bf16 v[82:85], v[182:185], v[206:209], v[82:85]
	v_mfma_f32_16x16x32_bf16 v[70:73], v[174:177], v[236:239], v[70:73]
	v_mfma_f32_16x16x32_bf16 v[66:69], v[182:185], v[236:239], v[66:69]
	s_barrier
	s_add_i32 s56, s56, s27
	v_lshl_add_u64 v[224:225], s[30:31], 0, v[132:133]
	s_mov_b32 m0, s56
	ds_read_b128 v[186:189], v157 offset:16384
	ds_read_b128 v[190:193], v157 offset:17408
	ds_read_b128 v[194:197], v157 offset:18432
	ds_read_b128 v[198:201], v157 offset:19456
	ds_read_b128 v[202:205], v157 offset:20480
	ds_read_b128 v[206:209], v157 offset:21504
	ds_read_b128 v[220:223], v157 offset:22528
	ds_read_b128 v[236:239], v157 offset:23552
	global_load_lds_dwordx4 v[224:225], off
	s_add_i32 m0, s56, 0x2000
	s_add_u32 s56, s30, 0x40000
	v_lshl_add_u64 v[230:231], s[30:31], 0, v[136:137]
	s_addc_u32 s57, s31, 0
	s_add_i32 s58, s58, s27
	global_load_lds_dwordx4 v[230:231], off
	v_lshl_add_u64 v[240:241], s[56:57], 0, v[132:133]
	s_mov_b32 m0, s58
	v_lshl_add_u64 v[242:243], s[34:35], 0, v[134:135]
	global_load_lds_dwordx4 v[240:241], off
	v_lshl_add_u64 v[240:241], s[56:57], 0, v[136:137]
	s_add_i32 m0, s58, 0x2000
	s_nop 0
	global_load_lds_dwordx4 v[240:241], off
	v_lshl_add_u64 v[240:241], s[34:35], 0, v[130:131]
	s_mov_b32 m0, s44
	s_nop 0
	global_load_lds_dwordx4 v[240:241], off
	s_mov_b32 m0, s45
	s_nop 0
	global_load_lds_dwordx4 v[242:243], off
	s_nop 0
	s_nop 0
	s_nop 0
	s_waitcnt vmcnt(8)
	s_waitcnt lgkmcnt(0)
	s_barrier
	s_waitcnt lgkmcnt(0)
	v_mfma_f32_16x16x32_bf16 v[62:65], v[142:145], v[186:189], 0
	v_mfma_f32_16x16x32_bf16 v[58:61], v[162:165], v[186:189], 0
	v_mfma_f32_16x16x32_bf16 v[46:49], v[142:145], v[194:197], 0
	v_mfma_f32_16x16x32_bf16 v[42:45], v[162:165], v[194:197], 0
	v_mfma_f32_16x16x32_bf16 v[30:33], v[142:145], v[202:205], 0
	v_mfma_f32_16x16x32_bf16 v[26:29], v[162:165], v[202:205], 0
	v_mfma_f32_16x16x32_bf16 v[14:17], v[142:145], v[220:223], 0
	v_mfma_f32_16x16x32_bf16 v[10:13], v[162:165], v[220:223], 0
	v_mfma_f32_16x16x32_bf16 v[62:65], v[158:161], v[190:193], v[62:65]
	v_mfma_f32_16x16x32_bf16 v[58:61], v[166:169], v[190:193], v[58:61]
	v_mfma_f32_16x16x32_bf16 v[46:49], v[158:161], v[198:201], v[46:49]
	v_mfma_f32_16x16x32_bf16 v[42:45], v[166:169], v[198:201], v[42:45]
	v_mfma_f32_16x16x32_bf16 v[30:33], v[158:161], v[206:209], v[30:33]
	v_mfma_f32_16x16x32_bf16 v[26:29], v[166:169], v[206:209], v[26:29]
	v_mfma_f32_16x16x32_bf16 v[14:17], v[158:161], v[236:239], v[14:17]
	v_mfma_f32_16x16x32_bf16 v[10:13], v[166:169], v[236:239], v[10:13]
	v_mfma_f32_16x16x32_bf16 v[54:57], v[170:173], v[186:189], 0
	v_mfma_f32_16x16x32_bf16 v[50:53], v[178:181], v[186:189], 0
	v_mfma_f32_16x16x32_bf16 v[38:41], v[170:173], v[194:197], 0
	v_mfma_f32_16x16x32_bf16 v[34:37], v[178:181], v[194:197], 0
	v_mfma_f32_16x16x32_bf16 v[22:25], v[170:173], v[202:205], 0
	v_mfma_f32_16x16x32_bf16 v[18:21], v[178:181], v[202:205], 0
	v_mfma_f32_16x16x32_bf16 v[6:9], v[170:173], v[220:223], 0
	v_mfma_f32_16x16x32_bf16 v[2:5], v[178:181], v[220:223], 0
	v_mfma_f32_16x16x32_bf16 v[54:57], v[174:177], v[190:193], v[54:57]
	v_mfma_f32_16x16x32_bf16 v[50:53], v[182:185], v[190:193], v[50:53]
	v_mfma_f32_16x16x32_bf16 v[38:41], v[174:177], v[198:201], v[38:41]
	v_mfma_f32_16x16x32_bf16 v[34:37], v[182:185], v[198:201], v[34:37]
	v_mfma_f32_16x16x32_bf16 v[22:25], v[174:177], v[206:209], v[22:25]
	v_mfma_f32_16x16x32_bf16 v[18:21], v[182:185], v[206:209], v[18:21]
	v_mfma_f32_16x16x32_bf16 v[6:9], v[174:177], v[236:239], v[6:9]
	v_mfma_f32_16x16x32_bf16 v[2:5], v[182:185], v[236:239], v[2:5]
	s_barrier
	s_add_i32 s56, 0, 0x18000
	s_add_i32 s57, 0, 0x1c000
	v_add_u32_e32 v166, s56, v147
	v_add_u32_e32 v182, s57, v147
	ds_read_b128 v[142:145], v166
	ds_read_b128 v[158:161], v166 offset:1024
	ds_read_b128 v[162:165], v166 offset:2048
	ds_read_b128 v[166:169], v166 offset:3072
	ds_read_b128 v[170:173], v182
	ds_read_b128 v[174:177], v182 offset:1024
	ds_read_b128 v[178:181], v182 offset:2048
	ds_read_b128 v[182:185], v182 offset:3072
	s_add_u32 s34, s34, 0x40000
	s_addc_u32 s35, s35, 0
	s_mov_b32 m0, s43
	v_lshl_add_u64 v[244:245], s[34:35], 0, v[130:131]
	ds_read_b128 v[186:189], v157 offset:32768
	ds_read_b128 v[190:193], v157 offset:33792
	ds_read_b128 v[194:197], v157 offset:34816
	ds_read_b128 v[198:201], v157 offset:35840
	ds_read_b128 v[202:205], v157 offset:36864
	ds_read_b128 v[206:209], v157 offset:37888
	ds_read_b128 v[220:223], v157 offset:38912
	ds_read_b128 v[236:239], v157 offset:39936
	global_load_lds_dwordx4 v[244:245], off
	v_lshl_add_u64 v[244:245], s[34:35], 0, v[134:135]
	s_mov_b32 m0, s46
	s_nop 0
	global_load_lds_dwordx4 v[244:245], off
	s_nop 0
	s_nop 0
	s_nop 0
	s_nop 0
	s_nop 0
	s_nop 0
	s_nop 0
	s_waitcnt vmcnt(8)
	s_waitcnt lgkmcnt(0)
	s_barrier
	s_waitcnt lgkmcnt(0)
	v_mfma_f32_16x16x32_bf16 v[126:129], v[142:145], v[186:189], v[126:129]
	v_mfma_f32_16x16x32_bf16 v[122:125], v[162:165], v[186:189], v[122:125]
	v_mfma_f32_16x16x32_bf16 v[110:113], v[142:145], v[194:197], v[110:113]
	v_mfma_f32_16x16x32_bf16 v[106:109], v[162:165], v[194:197], v[106:109]
	v_mfma_f32_16x16x32_bf16 v[94:97], v[142:145], v[202:205], v[94:97]
	v_mfma_f32_16x16x32_bf16 v[90:93], v[162:165], v[202:205], v[90:93]
	v_mfma_f32_16x16x32_bf16 v[78:81], v[142:145], v[220:223], v[78:81]
	v_mfma_f32_16x16x32_bf16 v[74:77], v[162:165], v[220:223], v[74:77]
	v_mfma_f32_16x16x32_bf16 v[126:129], v[158:161], v[190:193], v[126:129]
	v_mfma_f32_16x16x32_bf16 v[122:125], v[166:169], v[190:193], v[122:125]
	v_mfma_f32_16x16x32_bf16 v[110:113], v[158:161], v[198:201], v[110:113]
	v_mfma_f32_16x16x32_bf16 v[106:109], v[166:169], v[198:201], v[106:109]
	v_mfma_f32_16x16x32_bf16 v[94:97], v[158:161], v[206:209], v[94:97]
	v_mfma_f32_16x16x32_bf16 v[90:93], v[166:169], v[206:209], v[90:93]
	v_mfma_f32_16x16x32_bf16 v[78:81], v[158:161], v[236:239], v[78:81]
	v_mfma_f32_16x16x32_bf16 v[74:77], v[166:169], v[236:239], v[74:77]
	v_mfma_f32_16x16x32_bf16 v[118:121], v[170:173], v[186:189], v[118:121]
	v_mfma_f32_16x16x32_bf16 v[114:117], v[178:181], v[186:189], v[114:117]
	v_mfma_f32_16x16x32_bf16 v[102:105], v[170:173], v[194:197], v[102:105]
	v_mfma_f32_16x16x32_bf16 v[98:101], v[178:181], v[194:197], v[98:101]
	v_mfma_f32_16x16x32_bf16 v[86:89], v[170:173], v[202:205], v[86:89]
	v_mfma_f32_16x16x32_bf16 v[82:85], v[178:181], v[202:205], v[82:85]
	v_mfma_f32_16x16x32_bf16 v[70:73], v[170:173], v[220:223], v[70:73]
	v_mfma_f32_16x16x32_bf16 v[66:69], v[178:181], v[220:223], v[66:69]
	v_mfma_f32_16x16x32_bf16 v[118:121], v[174:177], v[190:193], v[118:121]
	v_mfma_f32_16x16x32_bf16 v[114:117], v[182:185], v[190:193], v[114:117]
	v_mfma_f32_16x16x32_bf16 v[102:105], v[174:177], v[198:201], v[102:105]
	v_mfma_f32_16x16x32_bf16 v[98:101], v[182:185], v[198:201], v[98:101]
	v_mfma_f32_16x16x32_bf16 v[86:89], v[174:177], v[206:209], v[86:89]
	v_mfma_f32_16x16x32_bf16 v[82:85], v[182:185], v[206:209], v[82:85]
	v_mfma_f32_16x16x32_bf16 v[70:73], v[174:177], v[236:239], v[70:73]
	v_mfma_f32_16x16x32_bf16 v[66:69], v[182:185], v[236:239], v[66:69]
	s_barrier
	s_add_i32 s34, s56, s27
	v_lshl_add_u64 v[224:225], v[224:225], 0, s[96:97]
	s_mov_b32 m0, s34
	ds_read_b128 v[186:189], v157 offset:49152
	ds_read_b128 v[190:193], v157 offset:50176
	ds_read_b128 v[194:197], v157 offset:51200
	ds_read_b128 v[198:201], v157 offset:52224
	ds_read_b128 v[202:205], v157 offset:53248
	ds_read_b128 v[206:209], v157 offset:54272
	ds_read_b128 v[220:223], v157 offset:55296
	ds_read_b128 v[236:239], v157 offset:56320
	global_load_lds_dwordx4 v[224:225], off
	s_add_i32 m0, s34, 0x2000
	s_add_u32 s30, s30, 0x40080
	v_lshl_add_u64 v[224:225], v[230:231], 0, s[96:97]
	s_addc_u32 s31, s31, 0
	s_add_i32 s34, s57, s27
	global_load_lds_dwordx4 v[224:225], off
	v_lshl_add_u64 v[224:225], s[30:31], 0, v[132:133]
	s_mov_b32 m0, s34
	s_nop 0
	global_load_lds_dwordx4 v[224:225], off
	v_lshl_add_u64 v[224:225], s[30:31], 0, v[136:137]
	s_add_i32 m0, s34, 0x2000
	s_nop 0
	global_load_lds_dwordx4 v[224:225], off
	v_lshl_add_u64 v[224:225], v[240:241], 0, s[96:97]
	s_mov_b32 m0, s47
	s_nop 0
	global_load_lds_dwordx4 v[224:225], off
	v_lshl_add_u64 v[224:225], v[242:243], 0, s[96:97]
	s_mov_b32 m0, s48
	s_nop 0
	global_load_lds_dwordx4 v[224:225], off
	s_nop 0
	s_nop 0
	s_waitcnt vmcnt(8)
	s_waitcnt lgkmcnt(0)
	s_barrier
	s_waitcnt lgkmcnt(0)
	v_mfma_f32_16x16x32_bf16 v[62:65], v[142:145], v[186:189], v[62:65]
	v_mfma_f32_16x16x32_bf16 v[58:61], v[162:165], v[186:189], v[58:61]
	v_mfma_f32_16x16x32_bf16 v[46:49], v[142:145], v[194:197], v[46:49]
	v_mfma_f32_16x16x32_bf16 v[42:45], v[162:165], v[194:197], v[42:45]
	v_mfma_f32_16x16x32_bf16 v[30:33], v[142:145], v[202:205], v[30:33]
	v_mfma_f32_16x16x32_bf16 v[26:29], v[162:165], v[202:205], v[26:29]
	v_mfma_f32_16x16x32_bf16 v[14:17], v[142:145], v[220:223], v[14:17]
	v_mfma_f32_16x16x32_bf16 v[10:13], v[162:165], v[220:223], v[10:13]
	v_mfma_f32_16x16x32_bf16 v[62:65], v[158:161], v[190:193], v[62:65]
	v_mfma_f32_16x16x32_bf16 v[58:61], v[166:169], v[190:193], v[58:61]
	v_mfma_f32_16x16x32_bf16 v[46:49], v[158:161], v[198:201], v[46:49]
	v_mfma_f32_16x16x32_bf16 v[42:45], v[166:169], v[198:201], v[42:45]
	v_mfma_f32_16x16x32_bf16 v[30:33], v[158:161], v[206:209], v[30:33]
	v_mfma_f32_16x16x32_bf16 v[26:29], v[166:169], v[206:209], v[26:29]
	v_mfma_f32_16x16x32_bf16 v[14:17], v[158:161], v[236:239], v[14:17]
	v_mfma_f32_16x16x32_bf16 v[10:13], v[166:169], v[236:239], v[10:13]
	v_mfma_f32_16x16x32_bf16 v[54:57], v[170:173], v[186:189], v[54:57]
	v_mfma_f32_16x16x32_bf16 v[50:53], v[178:181], v[186:189], v[50:53]
	v_mfma_f32_16x16x32_bf16 v[38:41], v[170:173], v[194:197], v[38:41]
	v_mfma_f32_16x16x32_bf16 v[34:37], v[178:181], v[194:197], v[34:37]
	v_mfma_f32_16x16x32_bf16 v[22:25], v[170:173], v[202:205], v[22:25]
	v_mfma_f32_16x16x32_bf16 v[18:21], v[178:181], v[202:205], v[18:21]
	v_mfma_f32_16x16x32_bf16 v[6:9], v[170:173], v[220:223], v[6:9]
	v_mfma_f32_16x16x32_bf16 v[2:5], v[178:181], v[220:223], v[2:5]
	v_mfma_f32_16x16x32_bf16 v[54:57], v[174:177], v[190:193], v[54:57]
	v_mfma_f32_16x16x32_bf16 v[50:53], v[182:185], v[190:193], v[50:53]
	v_mfma_f32_16x16x32_bf16 v[38:41], v[174:177], v[198:201], v[38:41]
	v_mfma_f32_16x16x32_bf16 v[34:37], v[182:185], v[198:201], v[34:37]
	v_mfma_f32_16x16x32_bf16 v[22:25], v[174:177], v[206:209], v[22:25]
	v_mfma_f32_16x16x32_bf16 v[18:21], v[182:185], v[206:209], v[18:21]
	v_mfma_f32_16x16x32_bf16 v[6:9], v[174:177], v[236:239], v[6:9]
	v_mfma_f32_16x16x32_bf16 v[2:5], v[182:185], v[236:239], v[2:5]
	s_barrier
	s_add_i32 s55, s55, 2
	s_add_u32 s38, s38, 0x100
	s_addc_u32 s39, s39, 0
	s_add_u32 s28, s28, 0x100
	s_addc_u32 s29, s29, 0
	s_cmp_gt_u32 s55, 13

.LBB0_291:
	s_cmp_lg_u32 s9, 0
	s_cselect_b64 s[28:29], -1, 0
	s_or_b64 s[28:29], s[16:17], s[28:29]
	s_and_b64 vcc, exec, s[28:29]
	s_cbranch_vccnz .LBB0_307
	s_and_saveexec_b64 s[28:29], s[4:5]
	s_cbranch_execz .LBB0_306
	v_readlane_b32 s19, v254, 9
	s_getreg_b32 s9, hwreg(HW_REG_XCC_ID, 0, 4)
	s_nop 0
	v_mov_b32_e32 v142, s19
	v_readlane_b32 s19, v254, 10
	ds_read_b32 v142, v142
	s_nop 0
	v_mov_b32_e32 v143, s19
	ds_read_b32 v143, v143
	s_waitcnt lgkmcnt(0)
	v_cmp_ne_u32_e32 vcc, 0, v143
	s_cbranch_vccnz .LBB0_305
	v_cmp_ne_u32_e32 vcc, v219, v142
	s_cbranch_vccnz .LBB0_305
	s_lshl_b32 s9, s9, 8
	s_and_b32 s9, s9, 0xf00
	s_add_u32 s30, s0, s9
	s_addc_u32 s31, s1, 0
	global_load_dword v143, v227, s[30:31] offset:1024 sc1
	s_add_u32 s30, s30, 0x3400
	s_addc_u32 s31, s31, 0
	s_waitcnt vmcnt(0)
	v_cmp_ne_u32_e32 vcc, v143, v142
	s_cbranch_vccnz .LBB0_305
	s_mov_b32 s9, 1
	s_branch .LBB0_297

.LBB0_362:
	s_ashr_i32 s23, s22, 31
	s_lshl_b64 s[24:25], s[22:23], 19
	s_add_u32 s24, s80, s24
	s_addc_u32 s25, s81, s25
	s_and_b64 s[26:27], s[6:7], exec
	s_cselect_b32 s23, s25, s35
	s_cselect_b32 s39, s24, s34
	s_ashr_i32 s21, s20, 31
	s_lshl_b64 s[26:27], s[20:21], 19
	s_add_u32 s26, s45, s26
	s_addc_u32 s27, s46, s27
	s_and_b64 s[36:37], s[6:7], exec
	s_cselect_b32 s21, s27, s31
	s_cselect_b32 s40, s26, s30
	s_add_u32 s41, s30, 0x100
	s_addc_u32 s43, s31, 0
	s_add_u32 s30, s34, 0x40080
	s_addc_u32 s31, s35, 0
	s_mov_b32 s56, -2
	s_cmp_lg_u32 s38, 0
	s_cbranch_scc1 .Lsw_pfx_skip
	s_and_saveexec_b64 s[100:101], s[4:5]
	s_cbranch_execz .Lsw_pfx_rest
	s_getreg_b32 s62, hwreg(HW_REG_XCC_ID, 0, 4)
	s_lshl_b32 s62, s62, 8
	s_and_b32 s62, s62, 0xf00
	s_add_u32 s62, s0, s62
	s_addc_u32 s63, s1, 0
	global_load_dword v219, v227, s[62:63] offset:1024 sc1

.Lsw_pfx_skip:
	s_add_u32 s34, s30, 0xfffc0080
	s_addc_u32 s35, s31, -1
	s_add_i32 s57, 0, 0x10000
	s_cmp_eq_u32 s56, 12
	s_cselect_b32 s37, s23, s35
	s_cselect_b32 s36, s39, s34
	v_add_u32_e32 v146, s57, v155
	s_cselect_b32 s35, s21, s43
	s_cselect_b32 s34, s40, s41
	s_add_i32 s60, 0, 0x14000
	ds_read_b128 v[142:145], v146
	ds_read_b128 v[168:171], v146 offset:1024
	ds_read_b128 v[172:175], v146 offset:2048
	ds_read_b128 v[176:179], v146 offset:3072
	v_add_u32_e32 v146, s60, v155
	ds_read_b128 v[180:183], v146
	ds_read_b128 v[184:187], v146 offset:1024
	ds_read_b128 v[188:191], v146 offset:2048
	ds_read_b128 v[192:195], v146 offset:3072
	v_lshl_add_u64 v[146:147], s[30:31], 0, v[140:141]
	s_add_i32 m0, s48, 0xc000
	ds_read_b128 v[196:199], v157
	ds_read_b128 v[200:203], v157 offset:1024
	ds_read_b128 v[204:207], v157 offset:2048
	ds_read_b128 v[220:223], v157 offset:3072
	ds_read_b128 v[236:239], v157 offset:4096
	ds_read_b128 v[240:243], v157 offset:5120
	ds_read_b128 v[244:247], v157 offset:6144
	ds_read_b128 v[248:251], v157 offset:7168
	global_load_lds_dwordx4 v[146:147], off
	v_lshl_add_u64 v[146:147], s[30:31], 0, v[138:139]
	s_add_i32 m0, s48, 0xe000
	s_nop 0
	global_load_lds_dwordx4 v[146:147], off
	s_nop 0
	s_nop 0
	s_nop 0
	s_nop 0
	s_nop 0
	s_nop 0
	s_nop 0
	s_nop 0
	s_nop 0
	s_nop 0
	s_nop 0
	s_nop 0
	s_nop 0
	s_nop 0
	s_nop 0
	s_nop 0
	s_nop 0
	s_nop 0
	s_nop 0
	s_nop 0
	s_nop 0
	s_nop 0
	s_waitcnt vmcnt(8)
	s_waitcnt lgkmcnt(0)
	s_barrier
	s_waitcnt lgkmcnt(0)
	v_mfma_f32_16x16x32_bf16 v[126:129], v[142:145], v[196:199], 0
	v_mfma_f32_16x16x32_bf16 v[118:121], v[172:175], v[196:199], 0
	v_mfma_f32_16x16x32_bf16 v[110:113], v[142:145], v[204:207], 0
	v_mfma_f32_16x16x32_bf16 v[102:105], v[172:175], v[204:207], 0
	v_mfma_f32_16x16x32_bf16 v[94:97], v[142:145], v[236:239], 0
	v_mfma_f32_16x16x32_bf16 v[86:89], v[172:175], v[236:239], 0
	v_mfma_f32_16x16x32_bf16 v[78:81], v[142:145], v[244:247], 0
	v_mfma_f32_16x16x32_bf16 v[70:73], v[172:175], v[244:247], 0
	v_mfma_f32_16x16x32_bf16 v[126:129], v[168:171], v[200:203], v[126:129]
	v_mfma_f32_16x16x32_bf16 v[118:121], v[176:179], v[200:203], v[118:121]
	v_mfma_f32_16x16x32_bf16 v[110:113], v[168:171], v[220:223], v[110:113]
	v_mfma_f32_16x16x32_bf16 v[102:105], v[176:179], v[220:223], v[102:105]
	v_mfma_f32_16x16x32_bf16 v[94:97], v[168:171], v[240:243], v[94:97]
	v_mfma_f32_16x16x32_bf16 v[86:89], v[176:179], v[240:243], v[86:89]
	v_mfma_f32_16x16x32_bf16 v[78:81], v[168:171], v[248:251], v[78:81]
	v_mfma_f32_16x16x32_bf16 v[70:73], v[176:179], v[248:251], v[70:73]
	v_mfma_f32_16x16x32_bf16 v[122:125], v[180:183], v[196:199], 0
	v_mfma_f32_16x16x32_bf16 v[114:117], v[188:191], v[196:199], 0
	v_mfma_f32_16x16x32_bf16 v[106:109], v[180:183], v[204:207], 0
	v_mfma_f32_16x16x32_bf16 v[98:101], v[188:191], v[204:207], 0
	v_mfma_f32_16x16x32_bf16 v[90:93], v[180:183], v[236:239], 0
	v_mfma_f32_16x16x32_bf16 v[82:85], v[188:191], v[236:239], 0
	v_mfma_f32_16x16x32_bf16 v[74:77], v[180:183], v[244:247], 0
	v_mfma_f32_16x16x32_bf16 v[66:69], v[188:191], v[244:247], 0
	v_mfma_f32_16x16x32_bf16 v[122:125], v[184:187], v[200:203], v[122:125]
	v_mfma_f32_16x16x32_bf16 v[114:117], v[192:195], v[200:203], v[114:117]
	v_mfma_f32_16x16x32_bf16 v[106:109], v[184:187], v[220:223], v[106:109]
	v_mfma_f32_16x16x32_bf16 v[98:101], v[192:195], v[220:223], v[98:101]
	v_mfma_f32_16x16x32_bf16 v[90:93], v[184:187], v[240:243], v[90:93]
	v_mfma_f32_16x16x32_bf16 v[82:85], v[192:195], v[240:243], v[82:85]
	v_mfma_f32_16x16x32_bf16 v[74:77], v[184:187], v[248:251], v[74:77]
	v_mfma_f32_16x16x32_bf16 v[66:69], v[192:195], v[248:251], v[66:69]
	s_barrier
	s_add_i32 s57, s57, s44
	v_lshl_add_u64 v[146:147], s[34:35], 0, v[134:135]
	s_mov_b32 m0, s57
	ds_read_b128 v[196:199], v157 offset:16384
	ds_read_b128 v[200:203], v157 offset:17408
	ds_read_b128 v[204:207], v157 offset:18432
	ds_read_b128 v[220:223], v157 offset:19456
	ds_read_b128 v[236:239], v157 offset:20480
	ds_read_b128 v[240:243], v157 offset:21504
	ds_read_b128 v[244:247], v157 offset:22528
	ds_read_b128 v[248:251], v157 offset:23552
	global_load_lds_dwordx4 v[146:147], off
	s_add_i32 m0, s57, 0x2000
	s_add_u32 s58, s34, 0x40000
	v_lshl_add_u64 v[208:209], s[34:35], 0, v[130:131]
	s_addc_u32 s59, s35, 0
	s_add_i32 s57, s60, s44
	global_load_lds_dwordx4 v[208:209], off
	v_lshl_add_u64 v[224:225], s[58:59], 0, v[134:135]
	s_mov_b32 m0, s57
	v_lshl_add_u64 v[230:231], s[36:37], 0, v[132:133]
	global_load_lds_dwordx4 v[224:225], off
	v_lshl_add_u64 v[224:225], s[58:59], 0, v[130:131]
	s_add_i32 m0, s57, 0x2000
	s_nop 0
	global_load_lds_dwordx4 v[224:225], off
	v_lshl_add_u64 v[224:225], s[36:37], 0, v[136:137]
	s_mov_b32 m0, s48
	s_nop 0
	global_load_lds_dwordx4 v[224:225], off
	s_mov_b32 m0, s49
	s_nop 0
	global_load_lds_dwordx4 v[230:231], off
	s_nop 0
	s_nop 0
	s_nop 0
	s_waitcnt vmcnt(8)
	s_waitcnt lgkmcnt(0)
	s_barrier
	s_waitcnt lgkmcnt(0)
	v_mfma_f32_16x16x32_bf16 v[62:65], v[142:145], v[196:199], 0
	v_mfma_f32_16x16x32_bf16 v[54:57], v[172:175], v[196:199], 0
	v_mfma_f32_16x16x32_bf16 v[46:49], v[142:145], v[204:207], 0
	v_mfma_f32_16x16x32_bf16 v[38:41], v[172:175], v[204:207], 0
	v_mfma_f32_16x16x32_bf16 v[30:33], v[142:145], v[236:239], 0
	v_mfma_f32_16x16x32_bf16 v[22:25], v[172:175], v[236:239], 0
	v_mfma_f32_16x16x32_bf16 v[14:17], v[142:145], v[244:247], 0
	v_mfma_f32_16x16x32_bf16 v[6:9], v[172:175], v[244:247], 0
	v_mfma_f32_16x16x32_bf16 v[62:65], v[168:171], v[200:203], v[62:65]
	v_mfma_f32_16x16x32_bf16 v[54:57], v[176:179], v[200:203], v[54:57]
	v_mfma_f32_16x16x32_bf16 v[46:49], v[168:171], v[220:223], v[46:49]
	v_mfma_f32_16x16x32_bf16 v[38:41], v[176:179], v[220:223], v[38:41]
	v_mfma_f32_16x16x32_bf16 v[30:33], v[168:171], v[240:243], v[30:33]
	v_mfma_f32_16x16x32_bf16 v[22:25], v[176:179], v[240:243], v[22:25]
	v_mfma_f32_16x16x32_bf16 v[14:17], v[168:171], v[248:251], v[14:17]
	v_mfma_f32_16x16x32_bf16 v[6:9], v[176:179], v[248:251], v[6:9]
	v_mfma_f32_16x16x32_bf16 v[58:61], v[180:183], v[196:199], 0
	v_mfma_f32_16x16x32_bf16 v[50:53], v[188:191], v[196:199], 0
	v_mfma_f32_16x16x32_bf16 v[42:45], v[180:183], v[204:207], 0
	v_mfma_f32_16x16x32_bf16 v[34:37], v[188:191], v[204:207], 0
	v_mfma_f32_16x16x32_bf16 v[26:29], v[180:183], v[236:239], 0
	v_mfma_f32_16x16x32_bf16 v[18:21], v[188:191], v[236:239], 0
	v_mfma_f32_16x16x32_bf16 v[10:13], v[180:183], v[244:247], 0
	v_mfma_f32_16x16x32_bf16 v[2:5], v[188:191], v[244:247], 0
	v_mfma_f32_16x16x32_bf16 v[58:61], v[184:187], v[200:203], v[58:61]
	v_mfma_f32_16x16x32_bf16 v[50:53], v[192:195], v[200:203], v[50:53]
	v_mfma_f32_16x16x32_bf16 v[42:45], v[184:187], v[220:223], v[42:45]
	v_mfma_f32_16x16x32_bf16 v[34:37], v[192:195], v[220:223], v[34:37]
	v_mfma_f32_16x16x32_bf16 v[26:29], v[184:187], v[240:243], v[26:29]
	v_mfma_f32_16x16x32_bf16 v[18:21], v[192:195], v[240:243], v[18:21]
	v_mfma_f32_16x16x32_bf16 v[10:13], v[184:187], v[248:251], v[10:13]
	v_mfma_f32_16x16x32_bf16 v[2:5], v[192:195], v[248:251], v[2:5]
	s_barrier
	s_add_i32 s57, 0, 0x18000
	v_add_u32_e32 v164, s57, v155
	s_add_i32 s58, 0, 0x1c000
	ds_read_b128 v[142:145], v164
	ds_read_b128 v[168:171], v164 offset:1024
	ds_read_b128 v[172:175], v164 offset:2048
	ds_read_b128 v[176:179], v164 offset:3072
	v_add_u32_e32 v164, s58, v155
	ds_read_b128 v[180:183], v164
	ds_read_b128 v[184:187], v164 offset:1024
	ds_read_b128 v[188:191], v164 offset:2048
	ds_read_b128 v[192:195], v164 offset:3072
	s_add_u32 s36, s36, 0x40000
	s_addc_u32 s37, s37, 0
	s_mov_b32 m0, s50
	v_lshl_add_u64 v[252:253], s[36:37], 0, v[136:137]
	ds_read_b128 v[196:199], v157 offset:32768
	ds_read_b128 v[200:203], v157 offset:33792
	ds_read_b128 v[204:207], v157 offset:34816
	ds_read_b128 v[220:223], v157 offset:35840
	ds_read_b128 v[236:239], v157 offset:36864
	ds_read_b128 v[240:243], v157 offset:37888
	ds_read_b128 v[244:247], v157 offset:38912
	ds_read_b128 v[248:251], v157 offset:39936
	global_load_lds_dwordx4 v[252:253], off
	v_lshl_add_u64 v[252:253], s[36:37], 0, v[132:133]
	s_mov_b32 m0, s51
	s_nop 0
	global_load_lds_dwordx4 v[252:253], off
	s_nop 0
	s_nop 0
	s_nop 0
	s_nop 0
	s_nop 0
	s_nop 0
	s_nop 0
	s_waitcnt vmcnt(8)
	s_waitcnt lgkmcnt(0)
	s_barrier
	s_waitcnt lgkmcnt(0)
	v_mfma_f32_16x16x32_bf16 v[126:129], v[142:145], v[196:199], v[126:129]
	v_mfma_f32_16x16x32_bf16 v[118:121], v[172:175], v[196:199], v[118:121]
	v_mfma_f32_16x16x32_bf16 v[110:113], v[142:145], v[204:207], v[110:113]
	v_mfma_f32_16x16x32_bf16 v[102:105], v[172:175], v[204:207], v[102:105]
	v_mfma_f32_16x16x32_bf16 v[94:97], v[142:145], v[236:239], v[94:97]
	v_mfma_f32_16x16x32_bf16 v[86:89], v[172:175], v[236:239], v[86:89]
	v_mfma_f32_16x16x32_bf16 v[78:81], v[142:145], v[244:247], v[78:81]
	v_mfma_f32_16x16x32_bf16 v[70:73], v[172:175], v[244:247], v[70:73]
	v_mfma_f32_16x16x32_bf16 v[126:129], v[168:171], v[200:203], v[126:129]
	v_mfma_f32_16x16x32_bf16 v[118:121], v[176:179], v[200:203], v[118:121]
	v_mfma_f32_16x16x32_bf16 v[110:113], v[168:171], v[220:223], v[110:113]
	v_mfma_f32_16x16x32_bf16 v[102:105], v[176:179], v[220:223], v[102:105]
	v_mfma_f32_16x16x32_bf16 v[94:97], v[168:171], v[240:243], v[94:97]
	v_mfma_f32_16x16x32_bf16 v[86:89], v[176:179], v[240:243], v[86:89]
	v_mfma_f32_16x16x32_bf16 v[78:81], v[168:171], v[248:251], v[78:81]
	v_mfma_f32_16x16x32_bf16 v[70:73], v[176:179], v[248:251], v[70:73]
	v_mfma_f32_16x16x32_bf16 v[122:125], v[180:183], v[196:199], v[122:125]
	v_mfma_f32_16x16x32_bf16 v[114:117], v[188:191], v[196:199], v[114:117]
	v_mfma_f32_16x16x32_bf16 v[106:109], v[180:183], v[204:207], v[106:109]
	v_mfma_f32_16x16x32_bf16 v[98:101], v[188:191], v[204:207], v[98:101]
	v_mfma_f32_16x16x32_bf16 v[90:93], v[180:183], v[236:239], v[90:93]
	v_mfma_f32_16x16x32_bf16 v[82:85], v[188:191], v[236:239], v[82:85]
	v_mfma_f32_16x16x32_bf16 v[74:77], v[180:183], v[244:247], v[74:77]
	v_mfma_f32_16x16x32_bf16 v[66:69], v[188:191], v[244:247], v[66:69]
	v_mfma_f32_16x16x32_bf16 v[122:125], v[184:187], v[200:203], v[122:125]
	v_mfma_f32_16x16x32_bf16 v[114:117], v[192:195], v[200:203], v[114:117]
	v_mfma_f32_16x16x32_bf16 v[106:109], v[184:187], v[220:223], v[106:109]
	v_mfma_f32_16x16x32_bf16 v[98:101], v[192:195], v[220:223], v[98:101]
	v_mfma_f32_16x16x32_bf16 v[90:93], v[184:187], v[240:243], v[90:93]
	v_mfma_f32_16x16x32_bf16 v[82:85], v[192:195], v[240:243], v[82:85]
	v_mfma_f32_16x16x32_bf16 v[74:77], v[184:187], v[248:251], v[74:77]
	v_mfma_f32_16x16x32_bf16 v[66:69], v[192:195], v[248:251], v[66:69]
	s_barrier
	s_add_i32 s36, s57, s44
	v_lshl_add_u64 v[146:147], v[146:147], 0, s[96:97]
	s_mov_b32 m0, s36
	ds_read_b128 v[196:199], v157 offset:49152
	ds_read_b128 v[200:203], v157 offset:50176
	ds_read_b128 v[204:207], v157 offset:51200
	ds_read_b128 v[220:223], v157 offset:52224
	ds_read_b128 v[236:239], v157 offset:53248
	ds_read_b128 v[240:243], v157 offset:54272
	ds_read_b128 v[244:247], v157 offset:55296
	ds_read_b128 v[248:251], v157 offset:56320
	global_load_lds_dwordx4 v[146:147], off
	s_add_i32 m0, s36, 0x2000
	s_add_u32 s34, s34, 0x40080
	v_lshl_add_u64 v[146:147], v[208:209], 0, s[96:97]
	s_addc_u32 s35, s35, 0
	s_add_i32 s36, s58, s44
	global_load_lds_dwordx4 v[146:147], off
	v_lshl_add_u64 v[146:147], s[34:35], 0, v[134:135]
	s_mov_b32 m0, s36
	s_nop 0
	global_load_lds_dwordx4 v[146:147], off
	v_lshl_add_u64 v[146:147], s[34:35], 0, v[130:131]
	s_add_i32 m0, s36, 0x2000
	s_nop 0
	global_load_lds_dwordx4 v[146:147], off
	v_lshl_add_u64 v[146:147], v[224:225], 0, s[96:97]
	s_mov_b32 m0, s52
	s_nop 0
	global_load_lds_dwordx4 v[146:147], off
	v_lshl_add_u64 v[146:147], v[230:231], 0, s[96:97]
	s_mov_b32 m0, s53
	s_nop 0
	global_load_lds_dwordx4 v[146:147], off
	s_nop 0
	s_nop 0
	s_waitcnt vmcnt(8)
	s_waitcnt lgkmcnt(0)
	s_barrier
	s_waitcnt lgkmcnt(0)
	v_mfma_f32_16x16x32_bf16 v[62:65], v[142:145], v[196:199], v[62:65]
	v_mfma_f32_16x16x32_bf16 v[54:57], v[172:175], v[196:199], v[54:57]
	v_mfma_f32_16x16x32_bf16 v[46:49], v[142:145], v[204:207], v[46:49]
	v_mfma_f32_16x16x32_bf16 v[38:41], v[172:175], v[204:207], v[38:41]
	v_mfma_f32_16x16x32_bf16 v[30:33], v[142:145], v[236:239], v[30:33]
	v_mfma_f32_16x16x32_bf16 v[22:25], v[172:175], v[236:239], v[22:25]
	v_mfma_f32_16x16x32_bf16 v[14:17], v[142:145], v[244:247], v[14:17]
	v_mfma_f32_16x16x32_bf16 v[6:9], v[172:175], v[244:247], v[6:9]
	v_mfma_f32_16x16x32_bf16 v[62:65], v[168:171], v[200:203], v[62:65]
	v_mfma_f32_16x16x32_bf16 v[54:57], v[176:179], v[200:203], v[54:57]
	v_mfma_f32_16x16x32_bf16 v[46:49], v[168:171], v[220:223], v[46:49]
	v_mfma_f32_16x16x32_bf16 v[38:41], v[176:179], v[220:223], v[38:41]
	v_mfma_f32_16x16x32_bf16 v[30:33], v[168:171], v[240:243], v[30:33]
	v_mfma_f32_16x16x32_bf16 v[22:25], v[176:179], v[240:243], v[22:25]
	v_mfma_f32_16x16x32_bf16 v[14:17], v[168:171], v[248:251], v[14:17]
	v_mfma_f32_16x16x32_bf16 v[6:9], v[176:179], v[248:251], v[6:9]
	v_mfma_f32_16x16x32_bf16 v[58:61], v[180:183], v[196:199], v[58:61]
	v_mfma_f32_16x16x32_bf16 v[50:53], v[188:191], v[196:199], v[50:53]
	v_mfma_f32_16x16x32_bf16 v[42:45], v[180:183], v[204:207], v[42:45]
	v_mfma_f32_16x16x32_bf16 v[34:37], v[188:191], v[204:207], v[34:37]
	v_mfma_f32_16x16x32_bf16 v[26:29], v[180:183], v[236:239], v[26:29]
	v_mfma_f32_16x16x32_bf16 v[18:21], v[188:191], v[236:239], v[18:21]
	v_mfma_f32_16x16x32_bf16 v[10:13], v[180:183], v[244:247], v[10:13]
	v_mfma_f32_16x16x32_bf16 v[2:5], v[188:191], v[244:247], v[2:5]
	v_mfma_f32_16x16x32_bf16 v[58:61], v[184:187], v[200:203], v[58:61]
	v_mfma_f32_16x16x32_bf16 v[50:53], v[192:195], v[200:203], v[50:53]
	v_mfma_f32_16x16x32_bf16 v[42:45], v[184:187], v[220:223], v[42:45]
	v_mfma_f32_16x16x32_bf16 v[34:37], v[192:195], v[220:223], v[34:37]
	v_mfma_f32_16x16x32_bf16 v[26:29], v[184:187], v[240:243], v[26:29]
	v_mfma_f32_16x16x32_bf16 v[18:21], v[192:195], v[240:243], v[18:21]
	v_mfma_f32_16x16x32_bf16 v[10:13], v[184:187], v[248:251], v[10:13]
	v_mfma_f32_16x16x32_bf16 v[2:5], v[192:195], v[248:251], v[2:5]
	s_barrier
	s_add_i32 s56, s56, 2
	s_add_u32 s41, s41, 0x100
	s_addc_u32 s43, s43, 0
	s_add_u32 s30, s30, 0x100
	s_addc_u32 s31, s31, 0
	s_cmp_gt_u32 s56, 13

.LBB0_366:
	s_cmp_lg_u32 s38, 0
	s_cselect_b64 s[30:31], -1, 0
	s_xor_b64 s[34:35], s[10:11], -1
	s_or_b64 s[30:31], s[34:35], s[30:31]
	s_and_b64 vcc, exec, s[30:31]
	s_cbranch_vccnz .LBB0_382
	s_and_saveexec_b64 s[30:31], s[4:5]
	s_cbranch_execz .LBB0_381
	v_readlane_b32 s23, v254, 9
	s_getreg_b32 s21, hwreg(HW_REG_XCC_ID, 0, 4)
	s_nop 0
	v_mov_b32_e32 v142, s23
	v_readlane_b32 s23, v254, 10
	ds_read_b32 v142, v142
	s_nop 0
	v_mov_b32_e32 v143, s23
	ds_read_b32 v143, v143
	s_waitcnt lgkmcnt(0)
	v_cmp_ne_u32_e32 vcc, 0, v143
	s_cbranch_vccnz .LBB0_380
	v_cmp_ne_u32_e32 vcc, v219, v142
	s_cbranch_vccnz .LBB0_380
	s_lshl_b32 s21, s21, 8
	s_and_b32 s21, s21, 0xf00
	s_add_u32 s34, s0, s21
	s_addc_u32 s35, s1, 0
	global_load_dword v143, v227, s[34:35] offset:1024 sc1
	s_add_u32 s34, s34, 0x3400
	s_addc_u32 s35, s35, 0
	s_waitcnt vmcnt(0)
	v_cmp_ne_u32_e32 vcc, v143, v142
	s_cbranch_vccnz .LBB0_380
	s_mov_b32 s21, 1
	s_branch .LBB0_372

.LBB0_476:
	s_add_i32 s63, s31, 2
	s_add_u32 s38, s28, s36
	s_addc_u32 s39, s29, s37
	s_add_u32 s64, s26, s36
	s_addc_u32 s65, s27, s37
	s_add_i32 s66, 0, 0x10000
	s_cmp_eq_u32 s59, s31
	s_cselect_b32 s39, s9, s39
	s_cselect_b32 s38, s8, s38
	s_cselect_b32 s65, s35, s65
	s_cselect_b32 s64, s34, s64
	s_add_i32 s31, 0, 0x14000
	v_add_u32_e32 v160, s66, v146
	v_add_u32_e32 v176, s31, v146
	ds_read_b128 v[148:151], v160
	ds_read_b128 v[152:155], v160 offset:1024
	ds_read_b128 v[156:159], v160 offset:2048
	ds_read_b128 v[160:163], v160 offset:3072
	ds_read_b128 v[164:167], v176
	ds_read_b128 v[168:171], v176 offset:1024
	ds_read_b128 v[172:175], v176 offset:2048
	ds_read_b128 v[176:179], v176 offset:3072
	v_lshl_add_u64 v[208:209], s[28:29], 0, v[142:143]
	s_add_i32 m0, s51, 0xc000
	ds_read_b128 v[180:183], v147
	ds_read_b128 v[184:187], v147 offset:1024
	ds_read_b128 v[188:191], v147 offset:2048
	ds_read_b128 v[192:195], v147 offset:3072
	ds_read_b128 v[196:199], v147 offset:4096
	ds_read_b128 v[200:203], v147 offset:5120
	ds_read_b128 v[204:207], v147 offset:6144
	ds_read_b128 v[220:223], v147 offset:7168
	global_load_lds_dwordx4 v[208:209], off
	v_lshl_add_u64 v[208:209], s[28:29], 0, v[144:145]
	s_add_i32 m0, s51, 0xe000
	s_nop 0
	global_load_lds_dwordx4 v[208:209], off
	s_nop 0
	s_nop 0
	s_nop 0
	s_nop 0
	s_nop 0
	s_nop 0
	s_nop 0
	s_nop 0
	s_nop 0
	s_nop 0
	s_nop 0
	s_nop 0
	s_nop 0
	s_nop 0
	s_nop 0
	s_nop 0
	s_nop 0
	s_nop 0
	s_nop 0
	s_nop 0
	s_nop 0
	s_nop 0
	s_nop 0
	s_nop 0
	s_nop 0
	s_nop 0
	s_waitcnt vmcnt(8)
	s_waitcnt lgkmcnt(0)
	s_barrier
	s_waitcnt lgkmcnt(0)
	v_mfma_f32_16x16x32_bf16 v[126:129], v[148:151], v[180:183], v[126:129]
	v_mfma_f32_16x16x32_bf16 v[122:125], v[156:159], v[180:183], v[122:125]
	v_mfma_f32_16x16x32_bf16 v[110:113], v[148:151], v[188:191], v[110:113]
	v_mfma_f32_16x16x32_bf16 v[106:109], v[156:159], v[188:191], v[106:109]
	v_mfma_f32_16x16x32_bf16 v[94:97], v[148:151], v[196:199], v[94:97]
	v_mfma_f32_16x16x32_bf16 v[90:93], v[156:159], v[196:199], v[90:93]
	v_mfma_f32_16x16x32_bf16 v[78:81], v[148:151], v[204:207], v[78:81]
	v_mfma_f32_16x16x32_bf16 v[74:77], v[156:159], v[204:207], v[74:77]
	v_mfma_f32_16x16x32_bf16 v[126:129], v[152:155], v[184:187], v[126:129]
	v_mfma_f32_16x16x32_bf16 v[122:125], v[160:163], v[184:187], v[122:125]
	v_mfma_f32_16x16x32_bf16 v[110:113], v[152:155], v[192:195], v[110:113]
	v_mfma_f32_16x16x32_bf16 v[106:109], v[160:163], v[192:195], v[106:109]
	v_mfma_f32_16x16x32_bf16 v[94:97], v[152:155], v[200:203], v[94:97]
	v_mfma_f32_16x16x32_bf16 v[90:93], v[160:163], v[200:203], v[90:93]
	v_mfma_f32_16x16x32_bf16 v[78:81], v[152:155], v[220:223], v[78:81]
	v_mfma_f32_16x16x32_bf16 v[74:77], v[160:163], v[220:223], v[74:77]
	v_mfma_f32_16x16x32_bf16 v[118:121], v[164:167], v[180:183], v[118:121]
	v_mfma_f32_16x16x32_bf16 v[114:117], v[172:175], v[180:183], v[114:117]
	v_mfma_f32_16x16x32_bf16 v[102:105], v[164:167], v[188:191], v[102:105]
	v_mfma_f32_16x16x32_bf16 v[98:101], v[172:175], v[188:191], v[98:101]
	v_mfma_f32_16x16x32_bf16 v[86:89], v[164:167], v[196:199], v[86:89]
	v_mfma_f32_16x16x32_bf16 v[82:85], v[172:175], v[196:199], v[82:85]
	v_mfma_f32_16x16x32_bf16 v[70:73], v[164:167], v[204:207], v[70:73]
	v_mfma_f32_16x16x32_bf16 v[66:69], v[172:175], v[204:207], v[66:69]
	v_mfma_f32_16x16x32_bf16 v[118:121], v[168:171], v[184:187], v[118:121]
	v_mfma_f32_16x16x32_bf16 v[114:117], v[176:179], v[184:187], v[114:117]
	v_mfma_f32_16x16x32_bf16 v[102:105], v[168:171], v[192:195], v[102:105]
	v_mfma_f32_16x16x32_bf16 v[98:101], v[176:179], v[192:195], v[98:101]
	v_mfma_f32_16x16x32_bf16 v[86:89], v[168:171], v[200:203], v[86:89]
	v_mfma_f32_16x16x32_bf16 v[82:85], v[176:179], v[200:203], v[82:85]
	v_mfma_f32_16x16x32_bf16 v[70:73], v[168:171], v[220:223], v[70:73]
	v_mfma_f32_16x16x32_bf16 v[66:69], v[176:179], v[220:223], v[66:69]
	s_barrier
	s_add_i32 s66, s66, s47
	v_lshl_add_u64 v[208:209], s[64:65], 0, v[132:133]
	s_mov_b32 m0, s66
	ds_read_b128 v[180:183], v147 offset:16384
	ds_read_b128 v[184:187], v147 offset:17408
	ds_read_b128 v[188:191], v147 offset:18432
	ds_read_b128 v[192:195], v147 offset:19456
	ds_read_b128 v[196:199], v147 offset:20480
	ds_read_b128 v[200:203], v147 offset:21504
	ds_read_b128 v[204:207], v147 offset:22528
	ds_read_b128 v[220:223], v147 offset:23552
	global_load_lds_dwordx4 v[208:209], off
	s_add_i32 m0, s66, 0x2000
	v_lshl_add_u64 v[224:225], s[64:65], 0, v[136:137]
	s_add_u32 s64, s64, s45
	s_addc_u32 s65, s65, 0
	s_add_i32 s31, s31, s47
	global_load_lds_dwordx4 v[224:225], off
	v_lshl_add_u64 v[230:231], s[64:65], 0, v[132:133]
	s_mov_b32 m0, s31
	v_lshl_add_u64 v[236:237], s[64:65], 0, v[136:137]
	global_load_lds_dwordx4 v[230:231], off
	s_add_i32 m0, s31, 0x2000
	v_lshl_add_u64 v[238:239], s[38:39], 0, v[130:131]
	global_load_lds_dwordx4 v[236:237], off
	s_mov_b32 m0, s51
	v_lshl_add_u64 v[240:241], s[38:39], 0, v[134:135]
	global_load_lds_dwordx4 v[238:239], off
	s_mov_b32 m0, s52
	s_nop 0
	global_load_lds_dwordx4 v[240:241], off
	s_nop 0
	s_nop 0
	s_nop 0
	s_nop 0
	s_nop 0
	s_nop 0
	s_waitcnt vmcnt(8)
	s_waitcnt lgkmcnt(0)
	s_barrier
	s_waitcnt lgkmcnt(0)
	v_mfma_f32_16x16x32_bf16 v[62:65], v[148:151], v[180:183], v[62:65]
	v_mfma_f32_16x16x32_bf16 v[58:61], v[156:159], v[180:183], v[58:61]
	v_mfma_f32_16x16x32_bf16 v[46:49], v[148:151], v[188:191], v[46:49]
	v_mfma_f32_16x16x32_bf16 v[42:45], v[156:159], v[188:191], v[42:45]
	v_mfma_f32_16x16x32_bf16 v[30:33], v[148:151], v[196:199], v[30:33]
	v_mfma_f32_16x16x32_bf16 v[26:29], v[156:159], v[196:199], v[26:29]
	v_mfma_f32_16x16x32_bf16 v[14:17], v[148:151], v[204:207], v[14:17]
	v_mfma_f32_16x16x32_bf16 v[10:13], v[156:159], v[204:207], v[10:13]
	v_mfma_f32_16x16x32_bf16 v[62:65], v[152:155], v[184:187], v[62:65]
	v_mfma_f32_16x16x32_bf16 v[58:61], v[160:163], v[184:187], v[58:61]
	v_mfma_f32_16x16x32_bf16 v[46:49], v[152:155], v[192:195], v[46:49]
	v_mfma_f32_16x16x32_bf16 v[42:45], v[160:163], v[192:195], v[42:45]
	v_mfma_f32_16x16x32_bf16 v[30:33], v[152:155], v[200:203], v[30:33]
	v_mfma_f32_16x16x32_bf16 v[26:29], v[160:163], v[200:203], v[26:29]
	v_mfma_f32_16x16x32_bf16 v[14:17], v[152:155], v[220:223], v[14:17]
	v_mfma_f32_16x16x32_bf16 v[10:13], v[160:163], v[220:223], v[10:13]
	v_mfma_f32_16x16x32_bf16 v[54:57], v[164:167], v[180:183], v[54:57]
	v_mfma_f32_16x16x32_bf16 v[50:53], v[172:175], v[180:183], v[50:53]
	v_mfma_f32_16x16x32_bf16 v[38:41], v[164:167], v[188:191], v[38:41]
	v_mfma_f32_16x16x32_bf16 v[34:37], v[172:175], v[188:191], v[34:37]
	v_mfma_f32_16x16x32_bf16 v[22:25], v[164:167], v[196:199], v[22:25]
	v_mfma_f32_16x16x32_bf16 v[18:21], v[172:175], v[196:199], v[18:21]
	v_mfma_f32_16x16x32_bf16 v[6:9], v[164:167], v[204:207], v[6:9]
	v_mfma_f32_16x16x32_bf16 v[2:5], v[172:175], v[204:207], v[2:5]
	v_mfma_f32_16x16x32_bf16 v[54:57], v[168:171], v[184:187], v[54:57]
	v_mfma_f32_16x16x32_bf16 v[50:53], v[176:179], v[184:187], v[50:53]
	v_mfma_f32_16x16x32_bf16 v[38:41], v[168:171], v[192:195], v[38:41]
	v_mfma_f32_16x16x32_bf16 v[34:37], v[176:179], v[192:195], v[34:37]
	v_mfma_f32_16x16x32_bf16 v[22:25], v[168:171], v[200:203], v[22:25]
	v_mfma_f32_16x16x32_bf16 v[18:21], v[176:179], v[200:203], v[18:21]
	v_mfma_f32_16x16x32_bf16 v[6:9], v[168:171], v[220:223], v[6:9]
	v_mfma_f32_16x16x32_bf16 v[2:5], v[176:179], v[220:223], v[2:5]
	s_barrier
	s_add_i32 s31, 0, 0x18000
	s_add_i32 s64, 0, 0x1c000
	v_add_u32_e32 v160, s31, v146
	v_add_u32_e32 v176, s64, v146
	ds_read_b128 v[148:151], v160
	ds_read_b128 v[152:155], v160 offset:1024
	ds_read_b128 v[156:159], v160 offset:2048
	ds_read_b128 v[160:163], v160 offset:3072
	ds_read_b128 v[164:167], v176
	ds_read_b128 v[168:171], v176 offset:1024
	ds_read_b128 v[172:175], v176 offset:2048
	ds_read_b128 v[176:179], v176 offset:3072
	s_add_u32 s38, s38, s45
	s_addc_u32 s39, s39, 0
	s_mov_b32 m0, s53
	v_lshl_add_u64 v[242:243], s[38:39], 0, v[130:131]
	ds_read_b128 v[180:183], v147 offset:32768
	ds_read_b128 v[184:187], v147 offset:33792
	ds_read_b128 v[188:191], v147 offset:34816
	ds_read_b128 v[192:195], v147 offset:35840
	ds_read_b128 v[196:199], v147 offset:36864
	ds_read_b128 v[200:203], v147 offset:37888
	ds_read_b128 v[204:207], v147 offset:38912
	ds_read_b128 v[220:223], v147 offset:39936
	global_load_lds_dwordx4 v[242:243], off
	v_lshl_add_u64 v[242:243], s[38:39], 0, v[134:135]
	s_mov_b32 m0, s54
	s_nop 0
	global_load_lds_dwordx4 v[242:243], off
	s_nop 0
	s_nop 0
	s_nop 0
	s_nop 0
	s_nop 0
	s_nop 0
	s_nop 0
	s_nop 0
	s_waitcnt vmcnt(8)
	s_waitcnt lgkmcnt(0)
	s_barrier
	s_waitcnt lgkmcnt(0)
	v_mfma_f32_16x16x32_bf16 v[126:129], v[148:151], v[180:183], v[126:129]
	v_mfma_f32_16x16x32_bf16 v[122:125], v[156:159], v[180:183], v[122:125]
	v_mfma_f32_16x16x32_bf16 v[110:113], v[148:151], v[188:191], v[110:113]
	v_mfma_f32_16x16x32_bf16 v[106:109], v[156:159], v[188:191], v[106:109]
	v_mfma_f32_16x16x32_bf16 v[94:97], v[148:151], v[196:199], v[94:97]
	v_mfma_f32_16x16x32_bf16 v[90:93], v[156:159], v[196:199], v[90:93]
	v_mfma_f32_16x16x32_bf16 v[78:81], v[148:151], v[204:207], v[78:81]
	v_mfma_f32_16x16x32_bf16 v[74:77], v[156:159], v[204:207], v[74:77]
	v_mfma_f32_16x16x32_bf16 v[126:129], v[152:155], v[184:187], v[126:129]
	v_mfma_f32_16x16x32_bf16 v[122:125], v[160:163], v[184:187], v[122:125]
	v_mfma_f32_16x16x32_bf16 v[110:113], v[152:155], v[192:195], v[110:113]
	v_mfma_f32_16x16x32_bf16 v[106:109], v[160:163], v[192:195], v[106:109]
	v_mfma_f32_16x16x32_bf16 v[94:97], v[152:155], v[200:203], v[94:97]
	v_mfma_f32_16x16x32_bf16 v[90:93], v[160:163], v[200:203], v[90:93]
	v_mfma_f32_16x16x32_bf16 v[78:81], v[152:155], v[220:223], v[78:81]
	v_mfma_f32_16x16x32_bf16 v[74:77], v[160:163], v[220:223], v[74:77]
	v_mfma_f32_16x16x32_bf16 v[118:121], v[164:167], v[180:183], v[118:121]
	v_mfma_f32_16x16x32_bf16 v[114:117], v[172:175], v[180:183], v[114:117]
	v_mfma_f32_16x16x32_bf16 v[102:105], v[164:167], v[188:191], v[102:105]
	v_mfma_f32_16x16x32_bf16 v[98:101], v[172:175], v[188:191], v[98:101]
	v_mfma_f32_16x16x32_bf16 v[86:89], v[164:167], v[196:199], v[86:89]
	v_mfma_f32_16x16x32_bf16 v[82:85], v[172:175], v[196:199], v[82:85]
	v_mfma_f32_16x16x32_bf16 v[70:73], v[164:167], v[204:207], v[70:73]
	v_mfma_f32_16x16x32_bf16 v[66:69], v[172:175], v[204:207], v[66:69]
	v_mfma_f32_16x16x32_bf16 v[118:121], v[168:171], v[184:187], v[118:121]
	v_mfma_f32_16x16x32_bf16 v[114:117], v[176:179], v[184:187], v[114:117]
	v_mfma_f32_16x16x32_bf16 v[102:105], v[168:171], v[192:195], v[102:105]
	v_mfma_f32_16x16x32_bf16 v[98:101], v[176:179], v[192:195], v[98:101]
	v_mfma_f32_16x16x32_bf16 v[86:89], v[168:171], v[200:203], v[86:89]
	v_mfma_f32_16x16x32_bf16 v[82:85], v[176:179], v[200:203], v[82:85]
	v_mfma_f32_16x16x32_bf16 v[70:73], v[168:171], v[220:223], v[70:73]
	v_mfma_f32_16x16x32_bf16 v[66:69], v[176:179], v[220:223], v[66:69]
	s_barrier
	s_add_i32 s31, s31, s47
	v_lshl_add_u64 v[208:209], v[208:209], 0, s[96:97]
	s_mov_b32 m0, s31
	ds_read_b128 v[180:183], v147 offset:49152
	ds_read_b128 v[184:187], v147 offset:50176
	ds_read_b128 v[188:191], v147 offset:51200
	ds_read_b128 v[192:195], v147 offset:52224
	ds_read_b128 v[196:199], v147 offset:53248
	ds_read_b128 v[200:203], v147 offset:54272
	ds_read_b128 v[204:207], v147 offset:55296
	ds_read_b128 v[220:223], v147 offset:56320
	global_load_lds_dwordx4 v[208:209], off
	v_lshl_add_u64 v[208:209], v[224:225], 0, s[96:97]
	s_add_i32 m0, s31, 0x2000
	s_add_i32 s31, s64, s47
	global_load_lds_dwordx4 v[208:209], off
	v_lshl_add_u64 v[208:209], v[230:231], 0, s[96:97]
	s_mov_b32 m0, s31
	s_nop 0
	global_load_lds_dwordx4 v[208:209], off
	v_lshl_add_u64 v[208:209], v[236:237], 0, s[96:97]
	s_add_i32 m0, s31, 0x2000
	s_nop 0
	global_load_lds_dwordx4 v[208:209], off
	v_lshl_add_u64 v[208:209], v[238:239], 0, s[96:97]
	s_mov_b32 m0, s57
	s_nop 0
	global_load_lds_dwordx4 v[208:209], off
	v_lshl_add_u64 v[208:209], v[240:241], 0, s[96:97]
	s_mov_b32 m0, s58
	s_nop 0
	global_load_lds_dwordx4 v[208:209], off
	s_nop 0
	s_nop 0
	s_nop 0
	s_nop 0
	s_nop 0
	s_waitcnt vmcnt(8)
	s_waitcnt lgkmcnt(0)
	s_barrier
	s_waitcnt lgkmcnt(0)
	v_mfma_f32_16x16x32_bf16 v[62:65], v[148:151], v[180:183], v[62:65]
	v_mfma_f32_16x16x32_bf16 v[58:61], v[156:159], v[180:183], v[58:61]
	v_mfma_f32_16x16x32_bf16 v[46:49], v[148:151], v[188:191], v[46:49]
	v_mfma_f32_16x16x32_bf16 v[42:45], v[156:159], v[188:191], v[42:45]
	v_mfma_f32_16x16x32_bf16 v[30:33], v[148:151], v[196:199], v[30:33]
	v_mfma_f32_16x16x32_bf16 v[26:29], v[156:159], v[196:199], v[26:29]
	v_mfma_f32_16x16x32_bf16 v[14:17], v[148:151], v[204:207], v[14:17]
	v_mfma_f32_16x16x32_bf16 v[10:13], v[156:159], v[204:207], v[10:13]
	v_mfma_f32_16x16x32_bf16 v[62:65], v[152:155], v[184:187], v[62:65]
	v_mfma_f32_16x16x32_bf16 v[58:61], v[160:163], v[184:187], v[58:61]
	v_mfma_f32_16x16x32_bf16 v[46:49], v[152:155], v[192:195], v[46:49]
	v_mfma_f32_16x16x32_bf16 v[42:45], v[160:163], v[192:195], v[42:45]
	v_mfma_f32_16x16x32_bf16 v[30:33], v[152:155], v[200:203], v[30:33]
	v_mfma_f32_16x16x32_bf16 v[26:29], v[160:163], v[200:203], v[26:29]
	v_mfma_f32_16x16x32_bf16 v[14:17], v[152:155], v[220:223], v[14:17]
	v_mfma_f32_16x16x32_bf16 v[10:13], v[160:163], v[220:223], v[10:13]
	v_mfma_f32_16x16x32_bf16 v[54:57], v[164:167], v[180:183], v[54:57]
	v_mfma_f32_16x16x32_bf16 v[50:53], v[172:175], v[180:183], v[50:53]
	v_mfma_f32_16x16x32_bf16 v[38:41], v[164:167], v[188:191], v[38:41]
	v_mfma_f32_16x16x32_bf16 v[34:37], v[172:175], v[188:191], v[34:37]
	v_mfma_f32_16x16x32_bf16 v[22:25], v[164:167], v[196:199], v[22:25]
	v_mfma_f32_16x16x32_bf16 v[18:21], v[172:175], v[196:199], v[18:21]
	v_mfma_f32_16x16x32_bf16 v[6:9], v[164:167], v[204:207], v[6:9]
	v_mfma_f32_16x16x32_bf16 v[2:5], v[172:175], v[204:207], v[2:5]
	v_mfma_f32_16x16x32_bf16 v[54:57], v[168:171], v[184:187], v[54:57]
	v_mfma_f32_16x16x32_bf16 v[50:53], v[176:179], v[184:187], v[50:53]
	v_mfma_f32_16x16x32_bf16 v[38:41], v[168:171], v[192:195], v[38:41]
	v_mfma_f32_16x16x32_bf16 v[34:37], v[176:179], v[192:195], v[34:37]
	v_mfma_f32_16x16x32_bf16 v[22:25], v[168:171], v[200:203], v[22:25]
	v_mfma_f32_16x16x32_bf16 v[18:21], v[176:179], v[200:203], v[18:21]
	v_mfma_f32_16x16x32_bf16 v[6:9], v[168:171], v[220:223], v[6:9]
	v_mfma_f32_16x16x32_bf16 v[2:5], v[176:179], v[220:223], v[2:5]
	s_barrier
	s_add_u32 s36, s36, 0x100
	s_addc_u32 s37, s37, 0
	v_lshl_add_u64 v[144:145], v[144:145], 0, s[2:3]
	v_lshl_add_u64 v[142:143], v[142:143], 0, s[2:3]
	s_cmp_ge_u32 s63, s56
	s_mov_b32 s31, s63
	s_cbranch_scc0 .LBB0_476
	s_and_b64 vcc, exec, s[6:7]
	s_cbranch_vccnz .LBB0_464
	v_mov_b32_e32 v2, 0
	s_mov_b32 s55, s61
	s_mov_b32 s50, s62
	s_mov_b64 s[26:27], s[34:35]
	s_mov_b64 s[28:29], s[8:9]
	s_mov_b32 s60, s30
	v_mov_b32_e32 v3, v2
	v_mov_b32_e32 v4, v2
	v_mov_b32_e32 v5, v2
	v_mov_b32_e32 v6, v2
	v_mov_b32_e32 v7, v2
	v_mov_b32_e32 v8, v2
	v_mov_b32_e32 v9, v2
	v_mov_b32_e32 v18, v2
	v_mov_b32_e32 v19, v2
	v_mov_b32_e32 v20, v2
	v_mov_b32_e32 v21, v2
	v_mov_b32_e32 v22, v2
	v_mov_b32_e32 v23, v2
	v_mov_b32_e32 v24, v2
	v_mov_b32_e32 v25, v2
	v_mov_b32_e32 v34, v2
	v_mov_b32_e32 v35, v2
	v_mov_b32_e32 v36, v2
	v_mov_b32_e32 v37, v2
	v_mov_b32_e32 v38, v2
	v_mov_b32_e32 v39, v2
	v_mov_b32_e32 v40, v2
	v_mov_b32_e32 v41, v2
	v_mov_b32_e32 v50, v2
	v_mov_b32_e32 v51, v2
	v_mov_b32_e32 v52, v2
	v_mov_b32_e32 v53, v2
	v_mov_b32_e32 v54, v2
	v_mov_b32_e32 v55, v2
	v_mov_b32_e32 v56, v2
	v_mov_b32_e32 v57, v2
	v_mov_b32_e32 v10, v2
	v_mov_b32_e32 v11, v2
	v_mov_b32_e32 v12, v2
	v_mov_b32_e32 v13, v2
	v_mov_b32_e32 v14, v2
	v_mov_b32_e32 v15, v2
	v_mov_b32_e32 v16, v2
	v_mov_b32_e32 v17, v2
	v_mov_b32_e32 v26, v2
	v_mov_b32_e32 v27, v2
	v_mov_b32_e32 v28, v2
	v_mov_b32_e32 v29, v2
	v_mov_b32_e32 v30, v2
	v_mov_b32_e32 v31, v2
	v_mov_b32_e32 v32, v2
	v_mov_b32_e32 v33, v2
	v_mov_b32_e32 v42, v2
	v_mov_b32_e32 v43, v2
	v_mov_b32_e32 v44, v2
	v_mov_b32_e32 v45, v2
	v_mov_b32_e32 v46, v2
	v_mov_b32_e32 v47, v2
	v_mov_b32_e32 v48, v2
	v_mov_b32_e32 v49, v2
	v_mov_b32_e32 v58, v2
	v_mov_b32_e32 v59, v2
	v_mov_b32_e32 v60, v2
	v_mov_b32_e32 v61, v2
	v_mov_b32_e32 v62, v2
	v_mov_b32_e32 v63, v2
	v_mov_b32_e32 v64, v2
	v_mov_b32_e32 v65, v2
	v_mov_b32_e32 v66, v2
	v_mov_b32_e32 v67, v2
	v_mov_b32_e32 v68, v2
	v_mov_b32_e32 v69, v2
	v_mov_b32_e32 v70, v2
	v_mov_b32_e32 v71, v2
	v_mov_b32_e32 v72, v2
	v_mov_b32_e32 v73, v2
	v_mov_b32_e32 v82, v2
	v_mov_b32_e32 v83, v2
	v_mov_b32_e32 v84, v2
	v_mov_b32_e32 v85, v2
	v_mov_b32_e32 v86, v2
	v_mov_b32_e32 v87, v2
	v_mov_b32_e32 v88, v2
	v_mov_b32_e32 v89, v2
	v_mov_b32_e32 v98, v2
	v_mov_b32_e32 v99, v2
	v_mov_b32_e32 v100, v2
	v_mov_b32_e32 v101, v2
	v_mov_b32_e32 v102, v2
	v_mov_b32_e32 v103, v2
	v_mov_b32_e32 v104, v2
	v_mov_b32_e32 v105, v2
	v_mov_b32_e32 v114, v2
	v_mov_b32_e32 v115, v2
	v_mov_b32_e32 v116, v2
	v_mov_b32_e32 v117, v2
	v_mov_b32_e32 v118, v2
	v_mov_b32_e32 v119, v2
	v_mov_b32_e32 v120, v2
	v_mov_b32_e32 v121, v2
	v_mov_b32_e32 v74, v2
	v_mov_b32_e32 v75, v2
	v_mov_b32_e32 v76, v2
	v_mov_b32_e32 v77, v2
	v_mov_b32_e32 v78, v2
	v_mov_b32_e32 v79, v2
	v_mov_b32_e32 v80, v2
	v_mov_b32_e32 v81, v2
	v_mov_b32_e32 v90, v2
	v_mov_b32_e32 v91, v2
	v_mov_b32_e32 v92, v2
	v_mov_b32_e32 v93, v2
	v_mov_b32_e32 v94, v2
	v_mov_b32_e32 v95, v2
	v_mov_b32_e32 v96, v2
	v_mov_b32_e32 v97, v2
	v_mov_b32_e32 v106, v2
	v_mov_b32_e32 v107, v2
	v_mov_b32_e32 v108, v2
	v_mov_b32_e32 v109, v2
	v_mov_b32_e32 v110, v2
	v_mov_b32_e32 v111, v2
	v_mov_b32_e32 v112, v2
	v_mov_b32_e32 v113, v2
	v_mov_b32_e32 v122, v2
	v_mov_b32_e32 v123, v2
	v_mov_b32_e32 v124, v2
	v_mov_b32_e32 v125, v2
	v_mov_b32_e32 v126, v2
	v_mov_b32_e32 v127, v2
	v_mov_b32_e32 v128, v2
	v_mov_b32_e32 v129, v2
	s_branch .LBB0_464
